# attention tile loop: one static s_setprio 1 for waves 4-7 before the loop, per-section priority toggles removed (on top of previous version)
# speedup vs baseline: 1.0041x; 1.0013x over previous
; __device__ __forceinline__ void attn_unit(Frame& F, int b, int h, int qb, const bf16* QKVU, bf16* ATT, float lam, const float* subln_g, const unsigned* kmaxw) {
;     ...
;     float m_run = 0.f, l_sum = 0.f;
;     bool started = false, wdone = false;
;     int slot = 0;
;     for (int t = NT - 1; t >= 0; --t) {
;         if (t > 0) asm volatile("s_waitcnt vmcnt(4)" ::: "memory"); else asm volatile("s_waitcnt vmcnt(0)" ::: "memory");
;         __builtin_amdgcn_s_barrier(); asm volatile("" ::: "memory");
.LBB0_509:
	s_or_b64 exec, exec, s[42:43]
	s_waitcnt lgkmcnt(0)
	s_lshr_b32 s42, s64, 3
	v_mov_b32_e32 v178, v174
	v_mov_b32_e32 v179, v174
	s_add_i32 s65, s42, -16
	v_add_u32_e32 v198, s33, v122
	s_add_i32 s64, s33, s22
	s_mov_b32 s66, 1
	s_mov_b32 s67, 0
	s_and_b64 vcc, exec, s[28:29]
	s_cbranch_vccz .Lattn_prio_skip
	s_setprio 1
.Lattn_prio_skip:
	s_branch .LBB0_511
.LBB0_510:
	s_and_b64 vcc, exec, s[42:43]
	s_cbranch_vccnz .LBB0_534

; __device__ __forceinline__ void attn_unit(Frame& F, int b, int h, int qb, const bf16* QKVU, bf16* ATT, float lam, const float* subln_g, const unsigned* kmaxw) {
;     ...
;             { const float base = slope2 * (float)(kv0 - q0) - m_run;
; #pragma unroll
;               for (int r = 0; r < 16; ++r) { p0[r] = ab[r] + base; p1[r] = p0[r] + 32.f * slope2; } }
;             __builtin_amdgcn_s_setprio(1);
; #pragma unroll
;             for (int d0 = 0; d0 < 4; ++d0) { const bf16x8 k0 = *(const LAS bf16x8*)(Kb + koff[d0]), k1 = *(const LAS bf16x8*)(Kb + 8192 + koff[d0]);
;                 p0 = __builtin_amdgcn_mfma_f32_32x32x16_bf16(k0, qr[d0], p0, 0, 0, 0); p1 = __builtin_amdgcn_mfma_f32_32x32x16_bf16(k1, qr[d0], p1, 0, 0, 0); }
;             __builtin_amdgcn_s_setprio(0);
;             if (kv0 + 63 > qw0) { const int qpos = qw0 + r32;
; #pragma unroll
;                 for (int r = 0; r < 16; ++r) { const int kv = kv0 + crow(r, hi); if (kv > qpos) p0[r] = -INFINITY; if (kv + 32 > qpos) p1[r] = -INFINITY; } }
;             float mx = fmaxf(fmaxf(p0[0], p0[1]), p1[0]), mx2 = fmaxf(fmaxf(p0[2], p0[3]), p1[1]);
;             mx = fmaxf(fmaxf(mx, p1[2]), p1[3]);
; #pragma unroll
;             for (int r = 4; r < 16; r += 4) { mx = fmaxf(fmaxf(mx, p0[r]), p0[r + 1]); mx2 = fmaxf(fmaxf(mx2, p0[r + 2]), p0[r + 3]); mx = fmaxf(fmaxf(mx, p1[r]), p1[r + 1]); mx2 = fmaxf(fmaxf(mx2, p1[r + 2]), p1[r + 3]); }
;             mx = fmaxf(mx, mx2);
;             mx = fmaxf(mx, __shfl_xor(mx, 32));
;             bool sub = false; float delta = 0.f;
;             if (!started) { delta = mx; started = true; sub = true; }
;             else if (__any(mx > THR_RESC)) { delta = fmaxf(mx, 0.f); sub = true; const float f = __builtin_amdgcn_exp2f(-delta); l_sum *= f;
; #pragma unroll
;                 for (int c = 0; c < 4; ++c)
; #pragma unroll
;                     for (int r = 0; r < 16; ++r) o[c][r] *= f; }
;             if (sub) { m_run += delta;
; #pragma unroll
;                 for (int r = 0; r < 16; ++r) { p0[r] -= delta; p1[r] -= delta; } }
;             float ls = 0.f, ls2 = 0.f;
; #pragma unroll
;             for (int r = 0; r < 16; ++r) { p0[r] = __builtin_amdgcn_exp2f(p0[r]); p1[r] = __builtin_amdgcn_exp2f(p1[r]); ls += p0[r]; ls2 += p1[r]; }
;             l_sum += ls + ls2;
;             bf16x8 pf[2][2];
; #pragma unroll
;             for (int s = 0; s < 2; ++s) { v4u a, c;
.LBB0_520:
	s_xor_b64 s[12:13], s[12:13], -1
	s_andn2_b64 vcc, exec, s[12:13]
	s_mov_b64 s[12:13], -1
	s_cbranch_vccnz .LBB0_530
	s_add_i32 s22, s33, s67
	s_cmp_gt_u32 s22, s9
	s_mov_b64 s[12:13], 0
	s_cbranch_scc1 .LBB0_530
	v_cvt_f32_i32_e32 v66, s67
	s_lshl_b32 s12, s66, 15
	v_mov_b32_e32 v175, v174
	s_add_i32 s12, s12, 0
	v_fma_f32 v80, v114, v66, -v176
	v_add_f32_e32 v66, v158, v80
	v_add_f32_e32 v67, v159, v80
	v_add_f32_e32 v68, v160, v80
	v_add_f32_e32 v69, v161, v80
	v_add_f32_e32 v70, v162, v80
	v_add_f32_e32 v71, v163, v80
	v_add_f32_e32 v72, v164, v80
	v_add_f32_e32 v73, v165, v80
	v_add_f32_e32 v74, v166, v80
	v_add_f32_e32 v75, v167, v80
	v_add_f32_e32 v76, v168, v80
	v_add_f32_e32 v77, v169, v80
	v_add_f32_e32 v78, v170, v80
	v_add_f32_e32 v79, v171, v80
	v_add_f32_e32 v81, v173, v80
	v_add_f32_e32 v80, v172, v80
	v_add_f32_e32 v94, v174, v78
	v_add_f32_e32 v95, v175, v79
	v_add_f32_e32 v96, v174, v80
	v_add_f32_e32 v97, v175, v81
	v_add_f32_e32 v92, v174, v76
	v_add_f32_e32 v93, v175, v77
	v_add_f32_e32 v90, v174, v74
	v_add_f32_e32 v91, v175, v75
	v_add_f32_e32 v88, v174, v72
	v_add_f32_e32 v89, v175, v73
	v_add_f32_e32 v86, v174, v70
	v_add_f32_e32 v87, v175, v71
	v_add_f32_e32 v84, v174, v68
	v_add_f32_e32 v85, v175, v69
	v_add_f32_e32 v82, v178, v66
	v_add_f32_e32 v83, v179, v67
	s_waitcnt lgkmcnt(0)
	v_mfma_f32_32x32x16_bf16 v[66:81], v[200:203], v[98:101], v[66:81]
	v_mfma_f32_32x32x16_bf16 v[66:81], v[218:221], v[102:105], v[66:81]
	v_mfma_f32_32x32x16_bf16 v[66:81], v[226:229], v[106:109], v[66:81]
	v_mfma_f32_32x32x16_bf16 v[66:81], v[238:241], v[110:113], v[66:81]
	v_mfma_f32_32x32x16_bf16 v[82:97], v[204:207], v[98:101], v[82:97]
	v_mfma_f32_32x32x16_bf16 v[82:97], v[222:225], v[102:105], v[82:97]
	v_mfma_f32_32x32x16_bf16 v[82:97], v[230:233], v[106:109], v[82:97]
	v_mfma_f32_32x32x16_bf16 v[82:97], v[242:245], v[110:113], v[82:97]
	v_add_u32_e32 v204, s12, v184
	v_add_u32_e32 v208, s12, v188
	v_add_u32_e32 v205, s12, v185
	v_add_u32_e32 v209, s12, v189
	v_add_u32_e32 v206, s12, v186
	v_add_u32_e32 v210, s12, v190
	v_add_u32_e32 v207, s12, v187
	v_add_u32_e32 v211, s12, v191
	ds_read_b64_tr_b16 v[218:219], v204 offset:16384
	ds_read_b64_tr_b16 v[220:221], v208 offset:16384
	ds_read_b64_tr_b16 v[222:223], v205 offset:16384
	ds_read_b64_tr_b16 v[224:225], v209 offset:16384
	ds_read_b64_tr_b16 v[226:227], v206 offset:16384
	ds_read_b64_tr_b16 v[228:229], v210 offset:16384
	ds_read_b64_tr_b16 v[230:231], v207 offset:16384
	ds_read_b64_tr_b16 v[232:233], v211 offset:16384
	ds_read_b64_tr_b16 v[238:239], v204 offset:20480
	ds_read_b64_tr_b16 v[240:241], v208 offset:20480
	ds_read_b64_tr_b16 v[242:243], v205 offset:20480
	ds_read_b64_tr_b16 v[244:245], v209 offset:20480
	ds_read_b64_tr_b16 v[246:247], v206 offset:20480
	ds_read_b64_tr_b16 v[248:249], v210 offset:20480
	ds_read_b64_tr_b16 v[212:213], v207 offset:20480
	ds_read_b64_tr_b16 v[214:215], v211 offset:20480
	s_add_i32 s22, s22, 63
	s_cmp_le_u32 s22, s62
	s_cbranch_scc1 .LBB0_524
	v_add_u32_e32 v120, s67, v198
	v_cmp_lt_u32_e32 vcc, v120, v155
	v_add_u32_e32 v175, 2, v120
	s_nop 2
	v_cndmask_b32_e32 v67, v197, v67, vcc
	v_cmp_le_u32_e32 vcc, v120, v155
	s_nop 1
	v_cndmask_b32_e32 v66, v197, v66, vcc
	v_cmp_lt_i32_e32 vcc, v120, v157
	s_nop 1
	v_cndmask_b32_e32 v83, v197, v83, vcc
	v_cmp_le_i32_e32 vcc, v120, v157
	s_nop 1
	v_cndmask_b32_e32 v82, v197, v82, vcc
	v_cmp_le_u32_e32 vcc, v175, v155
	s_nop 1
	v_cndmask_b32_e32 v68, v197, v68, vcc
	v_cmp_le_i32_e32 vcc, v175, v157
	v_add_u32_e32 v175, 3, v120
	s_nop 0
	v_cndmask_b32_e32 v84, v197, v84, vcc
	v_cmp_le_u32_e32 vcc, v175, v155
	s_nop 1
	v_cndmask_b32_e32 v69, v197, v69, vcc
	v_cmp_le_i32_e32 vcc, v175, v157
	v_add_u32_e32 v175, 8, v120
	s_nop 0
	v_cndmask_b32_e32 v85, v197, v85, vcc
	v_cmp_le_u32_e32 vcc, v175, v155
	s_nop 1
	v_cndmask_b32_e32 v70, v197, v70, vcc
	v_cmp_le_i32_e32 vcc, v175, v157
	v_add_u32_e32 v175, 9, v120
	s_nop 0
	v_cndmask_b32_e32 v86, v197, v86, vcc
	v_cmp_le_u32_e32 vcc, v175, v155
	s_nop 1
	v_cndmask_b32_e32 v71, v197, v71, vcc
	v_cmp_le_i32_e32 vcc, v175, v157
	v_add_u32_e32 v175, 10, v120
	s_nop 0
	v_cndmask_b32_e32 v87, v197, v87, vcc
	v_cmp_le_u32_e32 vcc, v175, v155
	s_nop 1
	v_cndmask_b32_e32 v72, v197, v72, vcc
	v_cmp_le_i32_e32 vcc, v175, v157
	v_add_u32_e32 v175, 11, v120
	s_nop 0
	v_cndmask_b32_e32 v88, v197, v88, vcc
	v_cmp_le_u32_e32 vcc, v175, v155
	s_nop 1
	v_cndmask_b32_e32 v73, v197, v73, vcc
	v_cmp_le_i32_e32 vcc, v175, v157
	v_add_u32_e32 v175, 16, v120
	s_nop 0
	v_cndmask_b32_e32 v89, v197, v89, vcc
	v_cmp_le_u32_e32 vcc, v175, v155
	s_nop 1
	v_cndmask_b32_e32 v74, v197, v74, vcc
	v_cmp_le_i32_e32 vcc, v175, v157
	v_add_u32_e32 v175, 17, v120
	s_nop 0
	v_cndmask_b32_e32 v90, v197, v90, vcc
	v_cmp_le_u32_e32 vcc, v175, v155
	s_nop 1
	v_cndmask_b32_e32 v75, v197, v75, vcc
	v_cmp_le_i32_e32 vcc, v175, v157
	v_add_u32_e32 v175, 18, v120
	s_nop 0
	v_cndmask_b32_e32 v91, v197, v91, vcc
	v_cmp_le_u32_e32 vcc, v175, v155
	s_nop 1
	v_cndmask_b32_e32 v76, v197, v76, vcc
	v_cmp_le_i32_e32 vcc, v175, v157
	v_add_u32_e32 v175, 19, v120
	s_nop 0
	v_cndmask_b32_e32 v92, v197, v92, vcc
	v_cmp_le_u32_e32 vcc, v175, v155
	s_nop 1
	v_cndmask_b32_e32 v77, v197, v77, vcc
	v_cmp_le_i32_e32 vcc, v175, v157
	v_add_u32_e32 v175, 24, v120
	s_nop 0
	v_cndmask_b32_e32 v93, v197, v93, vcc
	v_cmp_le_u32_e32 vcc, v175, v155
	s_nop 1
	v_cndmask_b32_e32 v78, v197, v78, vcc
	v_cmp_le_i32_e32 vcc, v175, v157
	v_add_u32_e32 v175, 25, v120
	s_nop 0
	v_cndmask_b32_e32 v94, v197, v94, vcc
	v_cmp_le_u32_e32 vcc, v175, v155
	s_nop 1
	v_cndmask_b32_e32 v79, v197, v79, vcc
	v_cmp_le_i32_e32 vcc, v175, v157
	v_add_u32_e32 v175, 26, v120
	v_add_u32_e32 v120, 27, v120
	v_cndmask_b32_e32 v95, v197, v95, vcc
	v_cmp_le_u32_e32 vcc, v175, v155
	s_nop 1
	v_cndmask_b32_e32 v80, v197, v80, vcc
	v_cmp_le_i32_e32 vcc, v175, v157
	s_nop 1
	v_cndmask_b32_e32 v96, v197, v96, vcc
	v_cmp_le_u32_e32 vcc, v120, v155
	s_nop 1
	v_cndmask_b32_e32 v81, v197, v81, vcc
	v_cmp_le_i32_e32 vcc, v120, v157
	s_nop 1
	v_cndmask_b32_e32 v97, v197, v97, vcc

; #define LAS __attribute__((address_space(3)))
; __device__ __forceinline__ unsigned pk2(float lo, float hi) { unsigned r; asm("v_cvt_pk_bf16_f32 %0, %1, %2" : "=v"(r) : "v"(lo), "v"(hi)); return r; }
; __device__ __forceinline__ void attn_unit(Frame& F, int b, int h, int qb, const bf16* QKVU, bf16* ATT, float lam, const float* subln_g, const unsigned* kmaxw) {
;     ...
;             if (sub) { m_run += delta;
; #pragma unroll
;                 for (int r = 0; r < 16; ++r) { p0[r] -= delta; p1[r] -= delta; } }
;             float ls = 0.f, ls2 = 0.f;
; #pragma unroll
;             for (int r = 0; r < 16; ++r) { p0[r] = __builtin_amdgcn_exp2f(p0[r]); p1[r] = __builtin_amdgcn_exp2f(p1[r]); ls += p0[r]; ls2 += p1[r]; }
;             l_sum += ls + ls2;
;             bf16x8 pf[2][2];
; #pragma unroll
;             for (int s = 0; s < 2; ++s) { v4u a, c;
;                 a.x = pk2(p0[8 * s + 0], p0[8 * s + 1]); a.y = pk2(p0[8 * s + 2], p0[8 * s + 3]); a.z = pk2(p0[8 * s + 4], p0[8 * s + 5]); a.w = pk2(p0[8 * s + 6], p0[8 * s + 7]);
;                 c.x = pk2(p1[8 * s + 0], p1[8 * s + 1]); c.y = pk2(p1[8 * s + 2], p1[8 * s + 3]); c.z = pk2(p1[8 * s + 4], p1[8 * s + 5]); c.w = pk2(p1[8 * s + 6], p1[8 * s + 7]);
;                 pf[0][s] = __builtin_bit_cast(bf16x8, a); pf[1][s] = __builtin_bit_cast(bf16x8, c); }
;             __builtin_amdgcn_s_setprio(1);
; #pragma unroll
;             for (int c = 0; c < 4; ++c) {
;                 const LAS unsigned char* vp0 = Vb + vb[c][0]; const LAS unsigned char* vp1 = Vb + vb[c][1];
; #pragma unroll
;                 for (int blk = 0; blk < 2; ++blk)
; #pragma unroll
;                     for (int s = 0; s < 2; ++s) {
;                         const s16x4 v0 = __builtin_bit_cast(s16x4, __builtin_amdgcn_ds_read_tr16_b64_v4i16((LAS s16x4*)(vp0 + 8192 * blk + 4096 * s)));
;                         const s16x4 v1 = __builtin_bit_cast(s16x4, __builtin_amdgcn_ds_read_tr16_b64_v4i16((LAS s16x4*)(vp1 + 8192 * blk + 4096 * s)));
;                         const bf16x8 vf = (bf16x8){v0[0], v0[1], v0[2], v0[3], v1[0], v1[1], v1[2], v1[3]};
;                         o[c] = __builtin_amdgcn_mfma_f32_32x32x16_bf16(vf, pf[blk][s], o[c], 0, 0, 0);
;                     }
;             }
;             __builtin_amdgcn_s_setprio(0);
;             wdone = __all(cbound + slope2 * (float)(kv0 - 1 - q0) - m_run < -THR_SKIP);
.LBB0_529:
	v_exp_f32_e32 v66, v66
	v_exp_f32_e32 v67, v67
	v_exp_f32_e32 v68, v68
	v_exp_f32_e32 v69, v69
	v_exp_f32_e32 v70, v70
	v_exp_f32_e32 v71, v71
	v_exp_f32_e32 v72, v72
	v_exp_f32_e32 v73, v73
	v_add_f32_e32 v200, v66, v67
	v_add_f32_e32 v201, v68, v69
	v_add_f32_e32 v200, v200, v70
	v_add_f32_e32 v201, v201, v71
	v_add_f32_e32 v200, v200, v72
	v_add_f32_e32 v201, v201, v73
	v_cvt_pk_bf16_f32 v66, v66, v67
	v_cvt_pk_bf16_f32 v67, v68, v69
	v_cvt_pk_bf16_f32 v68, v70, v71
	v_cvt_pk_bf16_f32 v69, v72, v73
	s_nop 1
	s_waitcnt lgkmcnt(8)
	v_mfma_f32_32x32x16_bf16 v[50:65], v[218:221], v[66:69], v[50:65]
	v_exp_f32_e32 v74, v74
	v_exp_f32_e32 v75, v75
	v_exp_f32_e32 v76, v76
	v_exp_f32_e32 v77, v77
	v_exp_f32_e32 v78, v78
	v_mfma_f32_32x32x16_bf16 v[34:49], v[222:225], v[66:69], v[34:49]
	v_exp_f32_e32 v79, v79
	v_exp_f32_e32 v80, v80
	v_exp_f32_e32 v81, v81
	v_add_f32_e32 v200, v200, v74
	v_add_f32_e32 v201, v201, v75
	v_mfma_f32_32x32x16_bf16 v[2:17], v[226:229], v[66:69], v[2:17]
	v_add_f32_e32 v200, v200, v76
	v_add_f32_e32 v201, v201, v77
	v_add_f32_e32 v200, v200, v78
	v_add_f32_e32 v201, v201, v79
	v_add_f32_e32 v200, v200, v80
	v_mfma_f32_32x32x16_bf16 v[18:33], v[230:233], v[66:69], v[18:33]
	v_add_f32_e32 v201, v201, v81
	v_cvt_pk_bf16_f32 v74, v74, v75
	v_cvt_pk_bf16_f32 v75, v76, v77
	v_cvt_pk_bf16_f32 v76, v78, v79
	v_cvt_pk_bf16_f32 v77, v80, v81
	ds_read_b64_tr_b16 v[218:219], v204 offset:24576
	ds_read_b64_tr_b16 v[220:221], v208 offset:24576
	ds_read_b64_tr_b16 v[222:223], v205 offset:24576
	ds_read_b64_tr_b16 v[224:225], v209 offset:24576
	ds_read_b64_tr_b16 v[226:227], v206 offset:24576
	ds_read_b64_tr_b16 v[228:229], v210 offset:24576
	ds_read_b64_tr_b16 v[230:231], v207 offset:24576
	ds_read_b64_tr_b16 v[232:233], v211 offset:24576
	s_nop 0
	s_waitcnt lgkmcnt(8)
	v_mfma_f32_32x32x16_bf16 v[50:65], v[238:241], v[74:77], v[50:65]
	v_exp_f32_e32 v82, v82
	v_exp_f32_e32 v83, v83
	v_exp_f32_e32 v84, v84
	v_exp_f32_e32 v85, v85
	v_exp_f32_e32 v86, v86
	v_mfma_f32_32x32x16_bf16 v[34:49], v[242:245], v[74:77], v[34:49]
	v_exp_f32_e32 v87, v87
	v_exp_f32_e32 v88, v88
	v_exp_f32_e32 v89, v89
	v_add_f32_e32 v200, v200, v82
	v_add_f32_e32 v201, v201, v83
	v_mfma_f32_32x32x16_bf16 v[2:17], v[246:249], v[74:77], v[2:17]
	v_add_f32_e32 v200, v200, v84
	v_add_f32_e32 v201, v201, v85
	v_add_f32_e32 v200, v200, v86
	v_add_f32_e32 v201, v201, v87
	v_add_f32_e32 v200, v200, v88
	v_mfma_f32_32x32x16_bf16 v[18:33], v[212:215], v[74:77], v[18:33]
	v_add_f32_e32 v201, v201, v89
	v_cvt_pk_bf16_f32 v70, v82, v83
	v_cvt_pk_bf16_f32 v71, v84, v85
	v_cvt_pk_bf16_f32 v72, v86, v87
	v_cvt_pk_bf16_f32 v73, v88, v89
	ds_read_b64_tr_b16 v[238:239], v204 offset:28672
	ds_read_b64_tr_b16 v[240:241], v208 offset:28672
	ds_read_b64_tr_b16 v[242:243], v205 offset:28672
	ds_read_b64_tr_b16 v[244:245], v209 offset:28672
	ds_read_b64_tr_b16 v[246:247], v206 offset:28672
	ds_read_b64_tr_b16 v[248:249], v210 offset:28672
	ds_read_b64_tr_b16 v[212:213], v207 offset:28672
	ds_read_b64_tr_b16 v[214:215], v211 offset:28672
	s_nop 0
	s_waitcnt lgkmcnt(8)
	v_mfma_f32_32x32x16_bf16 v[50:65], v[218:221], v[70:73], v[50:65]
	v_exp_f32_e32 v90, v90
	v_exp_f32_e32 v91, v91
	v_exp_f32_e32 v92, v92
	v_exp_f32_e32 v93, v93
	v_exp_f32_e32 v94, v94
	v_mfma_f32_32x32x16_bf16 v[34:49], v[222:225], v[70:73], v[34:49]
	v_exp_f32_e32 v95, v95
	v_exp_f32_e32 v96, v96
	v_exp_f32_e32 v97, v97
	v_add_f32_e32 v200, v200, v90
	v_add_f32_e32 v201, v201, v91
	v_mfma_f32_32x32x16_bf16 v[2:17], v[226:229], v[70:73], v[2:17]
	v_add_f32_e32 v200, v200, v92
	v_add_f32_e32 v201, v201, v93
	v_add_f32_e32 v200, v200, v94
	v_add_f32_e32 v201, v201, v95
	v_add_f32_e32 v200, v200, v96
	v_mfma_f32_32x32x16_bf16 v[18:33], v[230:233], v[70:73], v[18:33]
	v_add_f32_e32 v201, v201, v97
	v_cvt_pk_bf16_f32 v78, v90, v91
	v_cvt_pk_bf16_f32 v79, v92, v93
	v_cvt_pk_bf16_f32 v80, v94, v95
	v_cvt_pk_bf16_f32 v81, v96, v97
	s_nop 0
	s_waitcnt lgkmcnt(0)
	v_mfma_f32_32x32x16_bf16 v[50:65], v[238:241], v[78:81], v[50:65]
	v_mfma_f32_32x32x16_bf16 v[34:49], v[242:245], v[78:81], v[34:49]
	v_mfma_f32_32x32x16_bf16 v[2:17], v[246:249], v[78:81], v[2:17]
	v_mfma_f32_32x32x16_bf16 v[18:33], v[212:215], v[78:81], v[18:33]
	v_add_f32_e32 v120, v200, v201
	v_add_f32_e32 v177, v177, v120
	s_add_i32 s0, s64, s67
	v_cvt_f32_i32_e32 v66, s0
	s_mov_b64 s[0:1], -1
	v_fma_f32 v66, v114, v66, v151
	v_sub_f32_e32 v66, v66, v176
	v_cmp_gt_f32_e32 vcc, s60, v66
	s_cmp_eq_u64 vcc, exec
	s_cselect_b64 s[12:13], -1, 0

; #define LAS __attribute__((address_space(3)))
; __device__ __forceinline__ void attn_unit(Frame& F, int b, int h, int qb, const bf16* QKVU, bf16* ATT, float lam, const float* subln_g, const unsigned* kmaxw) {
;     ...
;     asm volatile("s_waitcnt vmcnt(0)" ::: "memory");
;     __syncthreads();
;     l_sum += __shfl_xor(l_sum, 32);
;     const float inv = 1.0f / l_sum;
;     LAS float* cmb = (LAS float*)lds;
;     if (jh == 1) {
; #pragma unroll
;         for (int c = 0; c < 4; ++c)
; #pragma unroll
;             for (int r = 0; r < 16; ++r) cmb[(qg * 64 + c * 16 + r) * 64 + lane] = o[c][r] * inv;
.LBB0_534:
	s_setprio 0
	ds_bpermute_b32 v66, v123, v177
	s_waitcnt vmcnt(0)
	s_waitcnt lgkmcnt(0)
	s_barrier
	v_add_f32_e32 v66, v177, v66
	v_div_scale_f32 v67, s[0:1], v66, v66, 1.0
	v_rcp_f32_e32 v68, v67
	v_div_scale_f32 v69, vcc, 1.0, v66, 1.0
	v_fma_f32 v70, -v67, v68, 1.0
	v_fmac_f32_e32 v68, v70, v68
	v_mul_f32_e32 v70, v69, v68
	v_fma_f32 v71, -v67, v70, v69
	v_fmac_f32_e32 v70, v71, v68
	v_fma_f32 v67, -v67, v70, v69
	v_div_fmas_f32 v67, v67, v68, v70
	s_andn2_b64 vcc, exec, s[28:29]
	v_div_fixup_f32 v72, v67, v66, 1.0
	s_cbranch_vccnz .LBB0_536
	v_mul_f32_e32 v66, v50, v72
	v_mul_f32_e32 v67, v51, v72
	ds_write2st64_b32 v192, v66, v67 offset1:1
	v_mul_f32_e32 v66, v52, v72
	v_mul_f32_e32 v67, v53, v72
	ds_write2st64_b32 v192, v66, v67 offset0:2 offset1:3
	v_mul_f32_e32 v66, v54, v72
	v_mul_f32_e32 v67, v55, v72
	ds_write2st64_b32 v192, v66, v67 offset0:4 offset1:5
	v_mul_f32_e32 v66, v56, v72
	v_mul_f32_e32 v67, v57, v72
	ds_write2st64_b32 v192, v66, v67 offset0:6 offset1:7
	v_mul_f32_e32 v66, v58, v72
	v_mul_f32_e32 v67, v59, v72
	ds_write2st64_b32 v192, v66, v67 offset0:8 offset1:9
	v_mul_f32_e32 v66, v60, v72
	v_mul_f32_e32 v67, v61, v72
	ds_write2st64_b32 v192, v66, v67 offset0:10 offset1:11
	v_mul_f32_e32 v66, v62, v72
	v_mul_f32_e32 v67, v63, v72
	ds_write2st64_b32 v192, v66, v67 offset0:12 offset1:13
	v_mul_f32_e32 v66, v64, v72
	v_mul_f32_e32 v67, v65, v72
	ds_write2st64_b32 v192, v66, v67 offset0:14 offset1:15
	v_mul_f32_e32 v66, v34, v72
	v_mul_f32_e32 v67, v35, v72
	ds_write2st64_b32 v192, v66, v67 offset0:16 offset1:17
	v_mul_f32_e32 v66, v36, v72
	v_mul_f32_e32 v67, v37, v72
	ds_write2st64_b32 v192, v66, v67 offset0:18 offset1:19
	v_mul_f32_e32 v66, v38, v72
	v_mul_f32_e32 v67, v39, v72
	ds_write2st64_b32 v192, v66, v67 offset0:20 offset1:21
	v_mul_f32_e32 v66, v40, v72
	v_mul_f32_e32 v67, v41, v72
	ds_write2st64_b32 v192, v66, v67 offset0:22 offset1:23
	v_mul_f32_e32 v66, v42, v72
	v_mul_f32_e32 v67, v43, v72
	ds_write2st64_b32 v192, v66, v67 offset0:24 offset1:25
	v_mul_f32_e32 v66, v44, v72
	v_mul_f32_e32 v67, v45, v72
	ds_write2st64_b32 v192, v66, v67 offset0:26 offset1:27
	v_mul_f32_e32 v66, v46, v72
	v_mul_f32_e32 v67, v47, v72
	ds_write2st64_b32 v192, v66, v67 offset0:28 offset1:29
	v_mul_f32_e32 v66, v48, v72
	v_mul_f32_e32 v67, v49, v72
	ds_write2st64_b32 v192, v66, v67 offset0:30 offset1:31
	v_mul_f32_e32 v66, v2, v72
	v_mul_f32_e32 v67, v3, v72
	ds_write2st64_b32 v192, v66, v67 offset0:32 offset1:33
	v_mul_f32_e32 v66, v4, v72
	v_mul_f32_e32 v67, v5, v72
	ds_write2st64_b32 v192, v66, v67 offset0:34 offset1:35
	v_mul_f32_e32 v66, v6, v72
	v_mul_f32_e32 v67, v7, v72
	ds_write2st64_b32 v192, v66, v67 offset0:36 offset1:37
	v_mul_f32_e32 v66, v8, v72
	v_mul_f32_e32 v67, v9, v72
	ds_write2st64_b32 v192, v66, v67 offset0:38 offset1:39
	v_mul_f32_e32 v66, v10, v72
	v_mul_f32_e32 v67, v11, v72
	ds_write2st64_b32 v192, v66, v67 offset0:40 offset1:41
	v_mul_f32_e32 v66, v12, v72
	v_mul_f32_e32 v67, v13, v72
	ds_write2st64_b32 v192, v66, v67 offset0:42 offset1:43
	v_mul_f32_e32 v66, v14, v72
	v_mul_f32_e32 v67, v15, v72
	ds_write2st64_b32 v192, v66, v67 offset0:44 offset1:45
	v_mul_f32_e32 v66, v16, v72
	v_mul_f32_e32 v67, v17, v72
	ds_write2st64_b32 v192, v66, v67 offset0:46 offset1:47
	v_mul_f32_e32 v66, v18, v72
	v_mul_f32_e32 v67, v19, v72
	ds_write2st64_b32 v192, v66, v67 offset0:48 offset1:49
	v_mul_f32_e32 v66, v20, v72
	v_mul_f32_e32 v67, v21, v72
	ds_write2st64_b32 v192, v66, v67 offset0:50 offset1:51
	v_mul_f32_e32 v66, v22, v72
	v_mul_f32_e32 v67, v23, v72
	ds_write2st64_b32 v192, v66, v67 offset0:52 offset1:53
	v_mul_f32_e32 v66, v24, v72
	v_mul_f32_e32 v67, v25, v72
	ds_write2st64_b32 v192, v66, v67 offset0:54 offset1:55
	v_mul_f32_e32 v66, v26, v72
	v_mul_f32_e32 v67, v27, v72
	ds_write2st64_b32 v192, v66, v67 offset0:56 offset1:57
	v_mul_f32_e32 v66, v28, v72
	v_mul_f32_e32 v67, v29, v72
	ds_write2st64_b32 v192, v66, v67 offset0:58 offset1:59
	v_mul_f32_e32 v66, v30, v72
	v_mul_f32_e32 v67, v31, v72
	ds_write2st64_b32 v192, v66, v67 offset0:60 offset1:61
	v_mul_f32_e32 v66, v32, v72
	v_mul_f32_e32 v67, v33, v72
	ds_write2st64_b32 v192, v66, v67 offset0:62 offset1:63
